# W2 RESID epilogue: residual chunks loaded up front with one wait (same as the K=1024 RESID epilogue)
# speedup vs baseline: 1.0244x; 1.0106x over previous
; #define PG8_STAGE(bufoff, gbase, voff) do { _Pragma("unroll") for (int _i = 0; _i < 2; ++_i) \
;     __builtin_amdgcn_global_load_lds((const unsigned*)((const char*)(gbase) + (voff)[_i]), (LAS unsigned*)(lds + (bufoff) + ldsw + _i * 8192), 16, 0, 0); } while (0)
; #define PG8_LDA(dst, b, h) do { _Pragma("unroll") for (int m = 0; m < 4; ++m) _Pragma("unroll") for (int k = 0; k < 2; ++k) dst[m][k] = *(const LAS bf16x8*)(lds + PG8_SA(b, h) + aoff + m * 2048 + k * 1024); } while (0)
; #define PG8_LDB(dst, b, h) do { _Pragma("unroll") for (int n = 0; n < 2; ++n) _Pragma("unroll") for (int k = 0; k < 2; ++k) dst[n][k] = *(const LAS bf16x8*)(lds + PG8_SB(b, h) + boff + n * 2048 + k * 1024); } while (0)
; #define PG8_MMA(ai, bj, At, Bt) do { __builtin_amdgcn_s_setprio(1); _Pragma("unroll") for (int m = 0; m < 4; ++m) _Pragma("unroll") for (int n = 0; n < 2; ++n) _Pragma("unroll") for (int k = 0; k < 2; ++k) \
;     acc[ai][bj][m][n] = __builtin_amdgcn_mfma_f32_16x16x32_bf16(Bt[n][k], At[m][k], acc[ai][bj][m][n], 0, 0, 0); __builtin_amdgcn_s_setprio(0); } while (0)
; #define PG8_BAR __builtin_amdgcn_s_barrier()
; template <class Epi, class Sched>
; DI void gemm_phase(LAS unsigned char* lds, const Gemm g, const Sched& S, const Epi& E) {
;     ...
;     const bool has_next = S.next(ui + 1, nxt);
;     const char* nA = has_next ? (const char*)g.A + (size_t)nxt.pm * tstep : cA; const char* nB = has_next ? (const char*)g.Bt + (size_t)nxt.pn * tstep : cB;
; #pragma unroll 1
;     for (int t = 0; t < nt; t += 2) {
;       const bool last = (t == nt - 2);
;       const char* a1 = cA + (size_t)(t + 1) * kstep;
;       const char* a2 = last ? nA : cA + (size_t)(t + 2) * kstep; const char* b2 = last ? nB : cB + (size_t)(t + 2) * kstep;
;       const char* a3 = a2 + kstep; const char* b3 = b2 + kstep;
;       PG8_LDB(B0, 0, 0); PG8_SCHED; PG8_LDA(At, 0, 0); PG8_STAGE(PG8_SA(1, 1), a1 + hstep, voffA);
;       PG8_WAIT_L(8); PG8_BAR; PG8_WAIT_L(0); PG8_MMA(0, 0, At, B0); PG8_BAR; PG8_SCHED;
;       PG8_LDB(B1, 0, 1); PG8_STAGE(PG8_SB(0, 0), b2, voffB);
;       PG8_BAR; PG8_WAIT_L(0); PG8_MMA(0, 1, At, B1); PG8_BAR;
;       PG8_LDA(At, 0, 1); PG8_STAGE(PG8_SA(0, 0), a2, voffA);
;       PG8_BAR; PG8_WAIT_L(0); PG8_MMA(1, 0, At, B0); PG8_BAR; PG8_SCHED;
;       PG8_STAGE(PG8_SB(0, 1), b2 + hstep, voffB);
;       PG8_WAIT_V(6); PG8_BAR; PG8_MMA(1, 1, At, B1); PG8_BAR;
.LBB0_1905:
	s_add_u32 s22, s20, 0xfff00080
	s_addc_u32 s23, s21, -1
	s_add_i32 s51, 0, 0x10000
	ds_read_b128 v[138:141], v224
	ds_read_b128 v[148:151], v224 offset:1024
	ds_read_b128 v[152:155], v224 offset:2048
	ds_read_b128 v[156:159], v224 offset:3072
	s_cmp_eq_u32 s50, 60
	s_cselect_b32 s29, s11, s23
	s_cselect_b32 s28, s17, s22
	s_cselect_b32 s23, s7, s49
	s_cselect_b32 s22, s19, s24
	s_add_i32 m0, s39, 0xc000
	ds_read_b128 v[160:163], v147
	ds_read_b128 v[164:167], v147 offset:1024
	ds_read_b128 v[168:171], v147 offset:2048
	ds_read_b128 v[172:175], v147 offset:3072
	ds_read_b128 v[176:179], v147 offset:4096
	ds_read_b128 v[196:199], v147 offset:5120
	ds_read_b128 v[200:203], v147 offset:6144
	ds_read_b128 v[204:207], v147 offset:7168
	global_load_lds_dwordx4 v134, s[20:21]
	s_add_i32 m0, s39, 0xe000
	s_nop 0
	global_load_lds_dwordx4 v136, s[20:21]
	s_waitcnt lgkmcnt(8)
	s_barrier
	s_waitcnt lgkmcnt(0)
	v_mfma_f32_16x16x32_bf16 v[124:127], v[138:141], v[160:163], v[124:127]
	v_mfma_f32_16x16x32_bf16 v[120:123], v[152:155], v[160:163], v[120:123]
	v_mfma_f32_16x16x32_bf16 v[108:111], v[138:141], v[168:171], v[108:111]
	v_mfma_f32_16x16x32_bf16 v[104:107], v[152:155], v[168:171], v[104:107]
	v_mfma_f32_16x16x32_bf16 v[92:95], v[138:141], v[176:179], v[92:95]
	v_mfma_f32_16x16x32_bf16 v[88:91], v[152:155], v[176:179], v[88:91]
	v_mfma_f32_16x16x32_bf16 v[76:79], v[138:141], v[200:203], v[76:79]
	v_mfma_f32_16x16x32_bf16 v[72:75], v[152:155], v[200:203], v[72:75]
	v_mfma_f32_16x16x32_bf16 v[124:127], v[148:151], v[164:167], v[124:127]
	v_mfma_f32_16x16x32_bf16 v[120:123], v[156:159], v[164:167], v[120:123]
	v_mfma_f32_16x16x32_bf16 v[108:111], v[148:151], v[172:175], v[108:111]
	v_mfma_f32_16x16x32_bf16 v[104:107], v[156:159], v[172:175], v[104:107]
	v_mfma_f32_16x16x32_bf16 v[92:95], v[148:151], v[196:199], v[92:95]
	v_mfma_f32_16x16x32_bf16 v[88:91], v[156:159], v[196:199], v[88:91]
	v_mfma_f32_16x16x32_bf16 v[76:79], v[148:151], v[204:207], v[76:79]
	v_mfma_f32_16x16x32_bf16 v[72:75], v[156:159], v[204:207], v[72:75]
	s_barrier
	s_add_i32 s54, 0, 0x14000
	s_add_i32 s51, s51, s38
	ds_read_b128 v[208:211], v225
	ds_read_b128 v[212:215], v225 offset:1024
	ds_read_b128 v[216:219], v225 offset:2048
	ds_read_b128 v[220:223], v225 offset:3072
	s_add_u32 vcc_lo, s22, s0
	s_addc_u32 vcc_hi, s23, s1
	s_mov_b32 m0, s51
	s_nop 0
	global_load_lds_dwordx4 v144, s[22:23]
	s_add_i32 m0, s51, 0x2000
	s_nop 0
	global_load_lds_dwordx4 v132, s[22:23]
	s_barrier
	s_waitcnt lgkmcnt(0)
	v_mfma_f32_16x16x32_bf16 v[116:119], v[208:211], v[160:163], v[116:119]
	v_mfma_f32_16x16x32_bf16 v[112:115], v[216:219], v[160:163], v[112:115]
	v_mfma_f32_16x16x32_bf16 v[100:103], v[208:211], v[168:171], v[100:103]
	v_mfma_f32_16x16x32_bf16 v[96:99], v[216:219], v[168:171], v[96:99]
	v_mfma_f32_16x16x32_bf16 v[84:87], v[208:211], v[176:179], v[84:87]
	v_mfma_f32_16x16x32_bf16 v[80:83], v[216:219], v[176:179], v[80:83]
	v_mfma_f32_16x16x32_bf16 v[68:71], v[208:211], v[200:203], v[68:71]
	v_mfma_f32_16x16x32_bf16 v[64:67], v[216:219], v[200:203], v[64:67]
	v_mfma_f32_16x16x32_bf16 v[116:119], v[212:215], v[164:167], v[116:119]
	v_mfma_f32_16x16x32_bf16 v[112:115], v[220:223], v[164:167], v[112:115]
	v_mfma_f32_16x16x32_bf16 v[100:103], v[212:215], v[172:175], v[100:103]
	v_mfma_f32_16x16x32_bf16 v[96:99], v[220:223], v[172:175], v[96:99]
	v_mfma_f32_16x16x32_bf16 v[84:87], v[212:215], v[196:199], v[84:87]
	v_mfma_f32_16x16x32_bf16 v[80:83], v[220:223], v[196:199], v[80:83]
	v_mfma_f32_16x16x32_bf16 v[68:71], v[212:215], v[204:207], v[68:71]
	v_mfma_f32_16x16x32_bf16 v[64:67], v[220:223], v[204:207], v[64:67]
	s_mov_b32 m0, s39
	s_add_u32 s100, s28, s0
	s_addc_u32 s101, s29, s1
	s_barrier
	ds_read_b128 v[160:163], v147 offset:16384
	ds_read_b128 v[164:167], v147 offset:17408
	ds_read_b128 v[168:171], v147 offset:18432
	ds_read_b128 v[172:175], v147 offset:19456
	ds_read_b128 v[176:179], v147 offset:20480
	ds_read_b128 v[196:199], v147 offset:21504
	ds_read_b128 v[200:203], v147 offset:22528
	ds_read_b128 v[204:207], v147 offset:23552
	global_load_lds_dwordx4 v128, s[28:29]
	s_mov_b32 m0, s40
	s_nop 0
	global_load_lds_dwordx4 v130, s[28:29]
	s_barrier
	s_waitcnt lgkmcnt(0)
	v_mfma_f32_16x16x32_bf16 v[60:63], v[138:141], v[160:163], v[60:63]
	v_mfma_f32_16x16x32_bf16 v[56:59], v[152:155], v[160:163], v[56:59]
	v_mfma_f32_16x16x32_bf16 v[44:47], v[138:141], v[168:171], v[44:47]
	v_mfma_f32_16x16x32_bf16 v[40:43], v[152:155], v[168:171], v[40:43]
	v_mfma_f32_16x16x32_bf16 v[28:31], v[138:141], v[176:179], v[28:31]
	v_mfma_f32_16x16x32_bf16 v[24:27], v[152:155], v[176:179], v[24:27]
	v_mfma_f32_16x16x32_bf16 v[12:15], v[138:141], v[200:203], v[12:15]
	v_mfma_f32_16x16x32_bf16 v[8:11], v[152:155], v[200:203], v[8:11]
	v_mfma_f32_16x16x32_bf16 v[60:63], v[148:151], v[164:167], v[60:63]
	v_mfma_f32_16x16x32_bf16 v[56:59], v[156:159], v[164:167], v[56:59]
	v_mfma_f32_16x16x32_bf16 v[44:47], v[148:151], v[172:175], v[44:47]
	v_mfma_f32_16x16x32_bf16 v[40:43], v[156:159], v[172:175], v[40:43]
	v_mfma_f32_16x16x32_bf16 v[28:31], v[148:151], v[196:199], v[28:31]
	v_mfma_f32_16x16x32_bf16 v[24:27], v[156:159], v[196:199], v[24:27]
	v_mfma_f32_16x16x32_bf16 v[12:15], v[148:151], v[204:207], v[12:15]
	v_mfma_f32_16x16x32_bf16 v[8:11], v[156:159], v[204:207], v[8:11]
	s_barrier
	s_add_u32 s52, s22, 0x100000
	s_addc_u32 s53, s23, 0
	s_add_i32 s51, s54, s38
	s_mov_b32 m0, s51
	s_nop 0
	global_load_lds_dwordx4 v144, s[52:53]
	s_add_i32 m0, s51, 0x2000
	s_nop 0
	global_load_lds_dwordx4 v132, s[52:53]
	s_waitcnt vmcnt(6)
	s_barrier
; #define PG8_STAGE(bufoff, gbase, voff) do { _Pragma("unroll") for (int _i = 0; _i < 2; ++_i) \
;     __builtin_amdgcn_global_load_lds((const unsigned*)((const char*)(gbase) + (voff)[_i]), (LAS unsigned*)(lds + (bufoff) + ldsw + _i * 8192), 16, 0, 0); } while (0)
; #define PG8_LDA(dst, b, h) do { _Pragma("unroll") for (int m = 0; m < 4; ++m) _Pragma("unroll") for (int k = 0; k < 2; ++k) dst[m][k] = *(const LAS bf16x8*)(lds + PG8_SA(b, h) + aoff + m * 2048 + k * 1024); } while (0)
; #define PG8_LDB(dst, b, h) do { _Pragma("unroll") for (int n = 0; n < 2; ++n) _Pragma("unroll") for (int k = 0; k < 2; ++k) dst[n][k] = *(const LAS bf16x8*)(lds + PG8_SB(b, h) + boff + n * 2048 + k * 1024); } while (0)
; #define PG8_MMA(ai, bj, At, Bt) do { __builtin_amdgcn_s_setprio(1); _Pragma("unroll") for (int m = 0; m < 4; ++m) _Pragma("unroll") for (int n = 0; n < 2; ++n) _Pragma("unroll") for (int k = 0; k < 2; ++k) \
;     acc[ai][bj][m][n] = __builtin_amdgcn_mfma_f32_16x16x32_bf16(Bt[n][k], At[m][k], acc[ai][bj][m][n], 0, 0, 0); __builtin_amdgcn_s_setprio(0); } while (0)
; #define PG8_WAIT_V(n) asm volatile("s_waitcnt vmcnt(" #n ")" ::: "memory")
; #define PG8_WAIT_L(n) asm volatile("s_waitcnt lgkmcnt(" #n ")" ::: "memory")
; #define PG8_BAR __builtin_amdgcn_s_barrier()
; #define PG8_SCHED __builtin_amdgcn_sched_barrier(0)
; template <class Epi, class Sched>
; DI void gemm_phase(LAS unsigned char* lds, const Gemm g, const Sched& S, const Epi& E) {
;     ...
;       PG8_WAIT_V(6); PG8_BAR; PG8_MMA(1, 1, At, B1); PG8_BAR;
;       PG8_LDB(B0, 1, 0); PG8_SCHED; PG8_LDA(At, 1, 0); PG8_STAGE(PG8_SA(0, 1), a2 + hstep, voffA);
;       PG8_WAIT_L(8); PG8_BAR; PG8_WAIT_L(0); PG8_MMA(0, 0, At, B0); PG8_BAR; PG8_SCHED;
;       PG8_LDB(B1, 1, 1); PG8_STAGE(PG8_SB(1, 0), b3, voffB);
;       PG8_BAR; PG8_WAIT_L(0); PG8_MMA(0, 1, At, B1); PG8_BAR;
;       PG8_LDA(At, 1, 1); PG8_STAGE(PG8_SA(1, 0), a3, voffA);
;       PG8_BAR; PG8_WAIT_L(0); PG8_MMA(1, 0, At, B0); PG8_BAR; PG8_SCHED;
	v_mfma_f32_16x16x32_bf16 v[52:55], v[208:211], v[160:163], v[52:55]
	v_mfma_f32_16x16x32_bf16 v[48:51], v[216:219], v[160:163], v[48:51]
	v_mfma_f32_16x16x32_bf16 v[36:39], v[208:211], v[168:171], v[36:39]
	v_mfma_f32_16x16x32_bf16 v[32:35], v[216:219], v[168:171], v[32:35]
	v_mfma_f32_16x16x32_bf16 v[20:23], v[208:211], v[176:179], v[20:23]
	v_mfma_f32_16x16x32_bf16 v[16:19], v[216:219], v[176:179], v[16:19]
	v_mfma_f32_16x16x32_bf16 v[4:7], v[208:211], v[200:203], v[4:7]
	v_mfma_f32_16x16x32_bf16 v[0:3], v[216:219], v[200:203], v[0:3]
	v_mfma_f32_16x16x32_bf16 v[52:55], v[212:215], v[164:167], v[52:55]
	v_mfma_f32_16x16x32_bf16 v[48:51], v[220:223], v[164:167], v[48:51]
	v_mfma_f32_16x16x32_bf16 v[36:39], v[212:215], v[172:175], v[36:39]
	v_mfma_f32_16x16x32_bf16 v[32:35], v[220:223], v[172:175], v[32:35]
	v_mfma_f32_16x16x32_bf16 v[20:23], v[212:215], v[196:199], v[20:23]
	v_mfma_f32_16x16x32_bf16 v[16:19], v[220:223], v[196:199], v[16:19]
	v_mfma_f32_16x16x32_bf16 v[4:7], v[212:215], v[204:207], v[4:7]
	v_mfma_f32_16x16x32_bf16 v[0:3], v[220:223], v[204:207], v[0:3]
	s_add_i32 s51, 0, 0x18000
	s_barrier
	ds_read_b128 v[138:141], v226
	ds_read_b128 v[148:151], v226 offset:1024
	ds_read_b128 v[152:155], v226 offset:2048
	ds_read_b128 v[156:159], v226 offset:3072
	s_add_u32 s28, s28, 0x100000
	s_addc_u32 s29, s29, 0
	s_mov_b32 m0, s41
	ds_read_b128 v[160:163], v147 offset:32768
	ds_read_b128 v[164:167], v147 offset:33792
	ds_read_b128 v[168:171], v147 offset:34816
	ds_read_b128 v[172:175], v147 offset:35840
	ds_read_b128 v[176:179], v147 offset:36864
	ds_read_b128 v[196:199], v147 offset:37888
	ds_read_b128 v[200:203], v147 offset:38912
	ds_read_b128 v[204:207], v147 offset:39936
	global_load_lds_dwordx4 v128, s[28:29]
	s_mov_b32 m0, s42
	s_nop 0
	global_load_lds_dwordx4 v130, s[28:29]
	s_waitcnt lgkmcnt(8)
	s_barrier
	s_waitcnt lgkmcnt(0)
	v_mfma_f32_16x16x32_bf16 v[124:127], v[138:141], v[160:163], v[124:127]
	v_mfma_f32_16x16x32_bf16 v[120:123], v[152:155], v[160:163], v[120:123]
	v_mfma_f32_16x16x32_bf16 v[108:111], v[138:141], v[168:171], v[108:111]
	v_mfma_f32_16x16x32_bf16 v[104:107], v[152:155], v[168:171], v[104:107]
	v_mfma_f32_16x16x32_bf16 v[92:95], v[138:141], v[176:179], v[92:95]
	v_mfma_f32_16x16x32_bf16 v[88:91], v[152:155], v[176:179], v[88:91]
	v_mfma_f32_16x16x32_bf16 v[76:79], v[138:141], v[200:203], v[76:79]
	v_mfma_f32_16x16x32_bf16 v[72:75], v[152:155], v[200:203], v[72:75]
	v_mfma_f32_16x16x32_bf16 v[124:127], v[148:151], v[164:167], v[124:127]
	v_mfma_f32_16x16x32_bf16 v[120:123], v[156:159], v[164:167], v[120:123]
	v_mfma_f32_16x16x32_bf16 v[108:111], v[148:151], v[172:175], v[108:111]
	v_mfma_f32_16x16x32_bf16 v[104:107], v[156:159], v[172:175], v[104:107]
	v_mfma_f32_16x16x32_bf16 v[92:95], v[148:151], v[196:199], v[92:95]
	v_mfma_f32_16x16x32_bf16 v[88:91], v[156:159], v[196:199], v[88:91]
	v_mfma_f32_16x16x32_bf16 v[76:79], v[148:151], v[204:207], v[76:79]
	v_mfma_f32_16x16x32_bf16 v[72:75], v[156:159], v[204:207], v[72:75]
	s_barrier
	s_add_i32 s28, 0, 0x1c000
	s_add_i32 s29, s51, s38
	s_mov_b32 m0, s29
	ds_read_b128 v[208:211], v227
	ds_read_b128 v[212:215], v227 offset:1024
	ds_read_b128 v[216:219], v227 offset:2048
	ds_read_b128 v[220:223], v227 offset:3072
	global_load_lds_dwordx4 v144, vcc
	s_add_i32 m0, s29, 0x2000
	s_nop 0
	global_load_lds_dwordx4 v132, vcc
	s_barrier
	s_waitcnt lgkmcnt(0)
	v_mfma_f32_16x16x32_bf16 v[116:119], v[208:211], v[160:163], v[116:119]
	v_mfma_f32_16x16x32_bf16 v[112:115], v[216:219], v[160:163], v[112:115]
	v_mfma_f32_16x16x32_bf16 v[100:103], v[208:211], v[168:171], v[100:103]
	v_mfma_f32_16x16x32_bf16 v[96:99], v[216:219], v[168:171], v[96:99]
	v_mfma_f32_16x16x32_bf16 v[84:87], v[208:211], v[176:179], v[84:87]
	v_mfma_f32_16x16x32_bf16 v[80:83], v[216:219], v[176:179], v[80:83]
	v_mfma_f32_16x16x32_bf16 v[68:71], v[208:211], v[200:203], v[68:71]
	v_mfma_f32_16x16x32_bf16 v[64:67], v[216:219], v[200:203], v[64:67]
	v_mfma_f32_16x16x32_bf16 v[116:119], v[212:215], v[164:167], v[116:119]
	v_mfma_f32_16x16x32_bf16 v[112:115], v[220:223], v[164:167], v[112:115]
	v_mfma_f32_16x16x32_bf16 v[100:103], v[212:215], v[172:175], v[100:103]
	v_mfma_f32_16x16x32_bf16 v[96:99], v[220:223], v[172:175], v[96:99]
	v_mfma_f32_16x16x32_bf16 v[84:87], v[212:215], v[196:199], v[84:87]
	v_mfma_f32_16x16x32_bf16 v[80:83], v[220:223], v[196:199], v[80:83]
	v_mfma_f32_16x16x32_bf16 v[68:71], v[212:215], v[204:207], v[68:71]
	v_mfma_f32_16x16x32_bf16 v[64:67], v[220:223], v[204:207], v[64:67]
	s_mov_b32 m0, s46
	s_barrier
	ds_read_b128 v[160:163], v147 offset:49152
	ds_read_b128 v[164:167], v147 offset:50176
	ds_read_b128 v[168:171], v147 offset:51200
	ds_read_b128 v[172:175], v147 offset:52224
	ds_read_b128 v[176:179], v147 offset:53248
	ds_read_b128 v[196:199], v147 offset:54272
	ds_read_b128 v[200:203], v147 offset:55296
	ds_read_b128 v[204:207], v147 offset:56320
	global_load_lds_dwordx4 v128, s[100:101]
	s_mov_b32 m0, s47
	s_nop 0
	global_load_lds_dwordx4 v130, s[100:101]
	s_barrier
	s_waitcnt lgkmcnt(0)
	v_mfma_f32_16x16x32_bf16 v[60:63], v[138:141], v[160:163], v[60:63]
	v_mfma_f32_16x16x32_bf16 v[56:59], v[152:155], v[160:163], v[56:59]
	v_mfma_f32_16x16x32_bf16 v[44:47], v[138:141], v[168:171], v[44:47]
	v_mfma_f32_16x16x32_bf16 v[40:43], v[152:155], v[168:171], v[40:43]
	v_mfma_f32_16x16x32_bf16 v[28:31], v[138:141], v[176:179], v[28:31]
	v_mfma_f32_16x16x32_bf16 v[24:27], v[152:155], v[176:179], v[24:27]
	v_mfma_f32_16x16x32_bf16 v[12:15], v[138:141], v[200:203], v[12:15]
	v_mfma_f32_16x16x32_bf16 v[8:11], v[152:155], v[200:203], v[8:11]
	v_mfma_f32_16x16x32_bf16 v[60:63], v[148:151], v[164:167], v[60:63]
	v_mfma_f32_16x16x32_bf16 v[56:59], v[156:159], v[164:167], v[56:59]
	v_mfma_f32_16x16x32_bf16 v[44:47], v[148:151], v[172:175], v[44:47]
	v_mfma_f32_16x16x32_bf16 v[40:43], v[156:159], v[172:175], v[40:43]
	v_mfma_f32_16x16x32_bf16 v[28:31], v[148:151], v[196:199], v[28:31]
	v_mfma_f32_16x16x32_bf16 v[24:27], v[156:159], v[196:199], v[24:27]
	v_mfma_f32_16x16x32_bf16 v[12:15], v[148:151], v[204:207], v[12:15]
	v_mfma_f32_16x16x32_bf16 v[8:11], v[156:159], v[204:207], v[8:11]
	s_barrier
; template <class Epi, class Sched>
; DI void gemm_phase(LAS unsigned char* lds, const Gemm g, const Sched& S, const Epi& E) {
;     ...
;       PG8_STAGE(PG8_SB(1, 1), b3 + hstep, voffB);
;       PG8_WAIT_V(6); PG8_BAR; PG8_MMA(1, 1, At, B1); PG8_BAR;
;     }
;   DI void operator()(const f32x4 (&acc)[2][2][4][2], const pg8::Unit& u, int wr, int wc, int fr_, int fq_) const {
;     ...
;             } else if (EPI == EPI_RESID) {
;               if (n == 0) {
;                 const int f8 = u.pn * 256 + bj * 128 + wc * 32 + 8 * fq;
;                 const f32x4 v1 = acc[ai][bj][m][1];
;                 f32x4 r0, r1;
;                 if (rsrc) {
;                   r0 = *(const f32x4*)(rsrc + (size_t)token * 1024 + f8); r1 = *(const f32x4*)(rsrc + (size_t)token * 1024 + f8 + 4);
;                 } else {
;                   const u32x4 xu = *(const u32x4*)(xr + (size_t)token * 1024 + f8);
;                   r0 = (f32x4){bf2f(xu.x & 0xffffu), bf2f(xu.x >> 16), bf2f(xu.y & 0xffffu), bf2f(xu.y >> 16)};
;                   r1 = (f32x4){bf2f(xu.z & 0xffffu), bf2f(xu.z >> 16), bf2f(xu.w & 0xffffu), bf2f(xu.w >> 16)};
;                 }
;                 r0 += v; r1 += v1;
;                 st_bf8(xr + (size_t)token * 1024 + f8, r0, r1, 1.f);
;                 ssq += r0[0] * r0[0] + r0[1] * r0[1] + r0[2] * r0[2] + r0[3] * r0[3] + r1[0] * r1[0] + r1[1] * r1[1] + r1[2] * r1[2] + r1[3] * r1[3];
;               }
;             } else {
;               if (n == 0) {
;                 const f32x4 v1 = acc[ai][bj][m][1];
;                 u32x4 o4;
;                 { const float t0 = fmaxf(v[0], 0.f) * rinv, t1 = fmaxf(v[1], 0.f) * rinv, t2 = fmaxf(v[2], 0.f) * rinv, t3 = fmaxf(v[3], 0.f) * rinv;
;                   o4.x = pack2(t0 * t0, t1 * t1); o4.y = pack2(t2 * t2, t3 * t3); }
;                 { const float t0 = fmaxf(v1[0], 0.f) * rinv, t1 = fmaxf(v1[1], 0.f) * rinv, t2 = fmaxf(v1[2], 0.f) * rinv, t3 = fmaxf(v1[3], 0.f) * rinv;
;                   o4.z = pack2(t0 * t0, t1 * t1); o4.w = pack2(t2 * t2, t3 * t3); }
;                 *(u32x4*)((u16*)big + (size_t)token * 4096 + u.pn * 256 + bj * 128 + wc * 32 + 8 * fq) = o4;
;               }
;             }
;           }
;         if (EPI == EPI_RESID) {
;           ssq += shx(ssq, 16, t_ & 63);
;           ssq += shx(ssq, 32, t_ & 63);
;           if (fq == 0) ss_out[(size_t)token * 16 + u.pn * 4 + wc] = ssq;
	s_add_u32 s22, s22, 0x100080
	s_addc_u32 s23, s23, 0
	s_add_i32 s28, s28, s38
	s_mov_b32 m0, s28
	s_nop 0
	global_load_lds_dwordx4 v144, s[22:23]
	s_add_i32 m0, s28, 0x2000
	s_nop 0
	global_load_lds_dwordx4 v132, s[22:23]
	s_waitcnt vmcnt(6)
	s_barrier
	v_mfma_f32_16x16x32_bf16 v[52:55], v[208:211], v[160:163], v[52:55]
	v_mfma_f32_16x16x32_bf16 v[48:51], v[216:219], v[160:163], v[48:51]
	v_mfma_f32_16x16x32_bf16 v[36:39], v[208:211], v[168:171], v[36:39]
	v_mfma_f32_16x16x32_bf16 v[32:35], v[216:219], v[168:171], v[32:35]
	v_mfma_f32_16x16x32_bf16 v[20:23], v[208:211], v[176:179], v[20:23]
	v_mfma_f32_16x16x32_bf16 v[16:19], v[216:219], v[176:179], v[16:19]
	v_mfma_f32_16x16x32_bf16 v[4:7], v[208:211], v[200:203], v[4:7]
	v_mfma_f32_16x16x32_bf16 v[0:3], v[216:219], v[200:203], v[0:3]
	v_mfma_f32_16x16x32_bf16 v[52:55], v[212:215], v[164:167], v[52:55]
	v_mfma_f32_16x16x32_bf16 v[48:51], v[220:223], v[164:167], v[48:51]
	v_mfma_f32_16x16x32_bf16 v[36:39], v[212:215], v[172:175], v[36:39]
	v_mfma_f32_16x16x32_bf16 v[32:35], v[220:223], v[172:175], v[32:35]
	v_mfma_f32_16x16x32_bf16 v[20:23], v[212:215], v[196:199], v[20:23]
	v_mfma_f32_16x16x32_bf16 v[16:19], v[220:223], v[196:199], v[16:19]
	v_mfma_f32_16x16x32_bf16 v[4:7], v[212:215], v[204:207], v[4:7]
	v_mfma_f32_16x16x32_bf16 v[0:3], v[220:223], v[204:207], v[0:3]
	s_add_i32 s50, s50, 2
	s_add_u32 s20, s20, 0x100
	s_addc_u32 s21, s21, 0
	s_add_u32 s24, s24, 0x100
	s_addc_u32 s49, s49, 0
	s_cmp_gt_u32 s50, 61
	s_barrier
	s_cbranch_scc0 .LBB0_1905
	s_lshl_b32 s7, s18, 8
	v_mov_b32_e32 v139, v182
	s_add_i32 s7, s7, s44
	s_nop 0
	v_and_or_b32 v140, v139, 15, s7
	s_lshl_b32 s7, s16, 8
	v_bfe_u32 v141, v139, 4, 2
	s_or_b32 s7, s7, s45
	v_lshl_or_b32 v138, v141, 3, s7
	v_cmp_eq_u32_e32 vcc, 0, v141
	v_ashrrev_i32_e32 v141, 31, v140
	v_lshlrev_b32_e32 v139, 2, v139
	s_movk_i32 s7, 0x80
	v_lshlrev_b64 v[142:143], 11, v[140:141]
	v_bitop3_b32 v149, v139, 64, v190 bitop3:0x6c
	v_bitop3_b32 v148, v139, s7, v190 bitop3:0x6c
	v_ashrrev_i32_e32 v139, 31, v138
	v_lshl_add_u64 v[142:143], s[4:5], 0, v[142:143]
	v_lshl_add_u64 v[142:143], v[138:139], 1, v[142:143]
	v_lshlrev_b32_e32 v250, 1, v138
	v_lshl_add_u32 v250, v140, 11, v250
	global_load_dwordx4 v[158:161], v250, s[4:5]
	global_load_dwordx4 v[162:165], v250, s[4:5] offset:256
	v_add_u32_e32 v250, 0x8000, v250
	global_load_dwordx4 v[166:169], v250, s[4:5]
	global_load_dwordx4 v[170:173], v250, s[4:5] offset:256
	v_add_u32_e32 v250, 0x8000, v250
	global_load_dwordx4 v[174:177], v250, s[4:5]
	global_load_dwordx4 v[178:181], v250, s[4:5] offset:256
	v_add_u32_e32 v250, 0x8000, v250
	global_load_dwordx4 v[196:199], v250, s[4:5]
	global_load_dwordx4 v[200:203], v250, s[4:5] offset:256
	v_add_u32_e32 v250, 0x28000, v250
	global_load_dwordx4 v[204:207], v250, s[4:5]
	global_load_dwordx4 v[208:211], v250, s[4:5] offset:256
	v_add_u32_e32 v250, 0x8000, v250
	global_load_dwordx4 v[212:215], v250, s[4:5]
	global_load_dwordx4 v[216:219], v250, s[4:5] offset:256
	v_add_u32_e32 v250, 0x8000, v250
	global_load_dwordx4 v[220:223], v250, s[4:5]
	global_load_dwordx4 v[224:227], v250, s[4:5] offset:256
	v_add_u32_e32 v250, 0x8000, v250
	global_load_dwordx4 v[228:231], v250, s[4:5]
	global_load_dwordx4 v[232:235], v250, s[4:5] offset:256
	s_lshl_b32 s16, s16, 2
	s_ashr_i32 s17, s16, 31
	s_waitcnt vmcnt(0)
	v_lshlrev_b32_e32 v154, 16, v158
	v_and_b32_e32 v155, 0xffff0000, v158
	v_lshlrev_b32_e32 v150, 16, v159
	v_and_b32_e32 v151, 0xffff0000, v159
	v_lshlrev_b32_e32 v156, 16, v160
	v_and_b32_e32 v157, 0xffff0000, v160
	v_lshlrev_b32_e32 v152, 16, v161
	v_and_b32_e32 v153, 0xffff0000, v161
	v_pk_add_f32 v[126:127], v[126:127], v[150:151]
	v_pk_add_f32 v[124:125], v[124:125], v[154:155]
	v_pk_add_f32 v[150:151], v[122:123], v[152:153]
	v_pk_add_f32 v[152:153], v[120:121], v[156:157]
	v_cvt_pk_bf16_f32 v120, v124, v125
	v_cvt_pk_bf16_f32 v121, v126, v127
	v_cvt_pk_bf16_f32 v122, v152, v153
	v_cvt_pk_bf16_f32 v123, v150, v151
	global_store_dwordx4 v[142:143], v[120:123], off
	v_mul_f32_e32 v154, v125, v125
	v_fmac_f32_e32 v154, v124, v124
	v_fmac_f32_e32 v154, v126, v126
	v_fmac_f32_e32 v154, v127, v127
	v_fmac_f32_e32 v154, v152, v152
	v_fmac_f32_e32 v154, v153, v153
	v_fmac_f32_e32 v154, v150, v150
	v_fmac_f32_e32 v154, v151, v151
	v_lshlrev_b32_e32 v124, 16, v162
	v_and_b32_e32 v125, 0xffff0000, v162
	v_lshlrev_b32_e32 v120, 16, v163
	v_and_b32_e32 v121, 0xffff0000, v163
	v_lshlrev_b32_e32 v126, 16, v164
	v_and_b32_e32 v127, 0xffff0000, v164
	v_lshlrev_b32_e32 v122, 16, v165
	v_and_b32_e32 v123, 0xffff0000, v165
	v_pk_add_f32 v[118:119], v[118:119], v[120:121]
	v_pk_add_f32 v[116:117], v[116:117], v[124:125]
	v_pk_add_f32 v[120:121], v[114:115], v[122:123]
	v_pk_add_f32 v[122:123], v[112:113], v[126:127]
	v_cvt_pk_bf16_f32 v112, v116, v117
	v_cvt_pk_bf16_f32 v113, v118, v119
	v_cvt_pk_bf16_f32 v114, v122, v123
	v_cvt_pk_bf16_f32 v115, v120, v121
	global_store_dwordx4 v[142:143], v[112:115], off offset:256
	s_nop 1
	v_mul_f32_e32 v112, v117, v117
	v_fmac_f32_e32 v112, v116, v116
	v_fmac_f32_e32 v112, v118, v118
	v_fmac_f32_e32 v112, v119, v119
	v_fmac_f32_e32 v112, v122, v122
	v_fmac_f32_e32 v112, v123, v123
	v_fmac_f32_e32 v112, v120, v120
	v_fmac_f32_e32 v112, v121, v121
	v_add_f32_e32 v112, v154, v112
	ds_bpermute_b32 v113, v149, v112
	s_waitcnt lgkmcnt(0)
	v_add_f32_e32 v112, v112, v113
	ds_bpermute_b32 v113, v148, v112
	s_and_saveexec_b64 s[18:19], vcc
	s_cbranch_execz .LBB0_1908
	s_waitcnt lgkmcnt(0)
	v_add_f32_e32 v114, v112, v113
	v_lshlrev_b64 v[112:113], 6, v[140:141]
	v_lshl_add_u64 v[112:113], s[2:3], 0, v[112:113]
	v_lshl_add_u64 v[112:113], s[16:17], 2, v[112:113]
	s_lshl_b32 s24, s43, 2
	v_lshl_add_u64 v[112:113], v[112:113], 0, s[24:25]
	global_store_dword v[112:113], v114, off
; DI float bf2f(unsigned v) { return __uint_as_float(v << 16); }
;   DI void operator()(const f32x4 (&acc)[2][2][4][2], const pg8::Unit& u, int wr, int wc, int fr_, int fq_) const {
;     ...
;             } else if (EPI == EPI_RESID) {
;               if (n == 0) {
;                 const int f8 = u.pn * 256 + bj * 128 + wc * 32 + 8 * fq;
;                 const f32x4 v1 = acc[ai][bj][m][1];
;                 f32x4 r0, r1;
;                 if (rsrc) {
;                   r0 = *(const f32x4*)(rsrc + (size_t)token * 1024 + f8); r1 = *(const f32x4*)(rsrc + (size_t)token * 1024 + f8 + 4);
;                 } else {
;                   const u32x4 xu = *(const u32x4*)(xr + (size_t)token * 1024 + f8);
;                   r0 = (f32x4){bf2f(xu.x & 0xffffu), bf2f(xu.x >> 16), bf2f(xu.y & 0xffffu), bf2f(xu.y >> 16)};
;                   r1 = (f32x4){bf2f(xu.z & 0xffffu), bf2f(xu.z >> 16), bf2f(xu.w & 0xffffu), bf2f(xu.w >> 16)};
;                 }
;                 r0 += v; r1 += v1;
;                 st_bf8(xr + (size_t)token * 1024 + f8, r0, r1, 1.f);
;                 ssq += r0[0] * r0[0] + r0[1] * r0[1] + r0[2] * r0[2] + r0[3] * r0[3] + r1[0] * r1[0] + r1[1] * r1[1] + r1[2] * r1[2] + r1[3] * r1[3];
;               }
;             } else {
;               if (n == 0) {
;                 const f32x4 v1 = acc[ai][bj][m][1];
;                 u32x4 o4;
;                 { const float t0 = fmaxf(v[0], 0.f) * rinv, t1 = fmaxf(v[1], 0.f) * rinv, t2 = fmaxf(v[2], 0.f) * rinv, t3 = fmaxf(v[3], 0.f) * rinv;
;                   o4.x = pack2(t0 * t0, t1 * t1); o4.y = pack2(t2 * t2, t3 * t3); }
;                 { const float t0 = fmaxf(v1[0], 0.f) * rinv, t1 = fmaxf(v1[1], 0.f) * rinv, t2 = fmaxf(v1[2], 0.f) * rinv, t3 = fmaxf(v1[3], 0.f) * rinv;
;                   o4.z = pack2(t0 * t0, t1 * t1); o4.w = pack2(t2 * t2, t3 * t3); }
;                 *(u32x4*)((u16*)big + (size_t)token * 4096 + u.pn * 256 + bj * 128 + wc * 32 + 8 * fq) = o4;
;               }
;             }
;           }
;         if (EPI == EPI_RESID) {
;           ssq += shx(ssq, 16, t_ & 63);
;           ssq += shx(ssq, 32, t_ & 63);
;           if (fq == 0) ss_out[(size_t)token * 16 + u.pn * 4 + wc] = ssq;
.LBB0_1908:
	s_or_b64 exec, exec, s[18:19]
	v_or_b32_e32 v112, 16, v140
	s_waitcnt lgkmcnt(0)
	v_ashrrev_i32_e32 v113, 31, v112
	v_lshlrev_b64 v[114:115], 11, v[112:113]
	v_lshl_add_u64 v[114:115], s[4:5], 0, v[114:115]
	v_lshl_add_u64 v[118:119], v[138:139], 1, v[114:115]
	v_lshlrev_b32_e32 v120, 16, v166
	v_and_b32_e32 v121, 0xffff0000, v166
	v_lshlrev_b32_e32 v114, 16, v167
	v_and_b32_e32 v115, 0xffff0000, v167
	v_lshlrev_b32_e32 v122, 16, v168
	v_and_b32_e32 v123, 0xffff0000, v168
	v_lshlrev_b32_e32 v116, 16, v169
	v_and_b32_e32 v117, 0xffff0000, v169
	v_pk_add_f32 v[110:111], v[110:111], v[114:115]
	v_pk_add_f32 v[108:109], v[108:109], v[120:121]
	v_pk_add_f32 v[114:115], v[106:107], v[116:117]
	v_pk_add_f32 v[116:117], v[104:105], v[122:123]
	v_cvt_pk_bf16_f32 v104, v108, v109
	v_cvt_pk_bf16_f32 v105, v110, v111
	v_cvt_pk_bf16_f32 v106, v116, v117
	v_cvt_pk_bf16_f32 v107, v114, v115
	global_store_dwordx4 v[118:119], v[104:107], off
	v_mul_f32_e32 v120, v109, v109
	v_fmac_f32_e32 v120, v108, v108
	v_fmac_f32_e32 v120, v110, v110
	v_fmac_f32_e32 v120, v111, v111
	v_fmac_f32_e32 v120, v116, v116
	v_fmac_f32_e32 v120, v117, v117
	v_fmac_f32_e32 v120, v114, v114
	v_fmac_f32_e32 v120, v115, v115
	v_lshlrev_b32_e32 v108, 16, v170
	v_and_b32_e32 v109, 0xffff0000, v170
	v_lshlrev_b32_e32 v104, 16, v171
	v_and_b32_e32 v105, 0xffff0000, v171
	v_lshlrev_b32_e32 v110, 16, v172
	v_and_b32_e32 v111, 0xffff0000, v172
	v_lshlrev_b32_e32 v106, 16, v173
	v_and_b32_e32 v107, 0xffff0000, v173
	v_pk_add_f32 v[102:103], v[102:103], v[104:105]
	v_pk_add_f32 v[100:101], v[100:101], v[108:109]
	v_pk_add_f32 v[104:105], v[98:99], v[106:107]
	v_pk_add_f32 v[106:107], v[96:97], v[110:111]
	v_cvt_pk_bf16_f32 v96, v100, v101
	v_cvt_pk_bf16_f32 v97, v102, v103
	v_cvt_pk_bf16_f32 v98, v106, v107
	v_cvt_pk_bf16_f32 v99, v104, v105
	global_store_dwordx4 v[118:119], v[96:99], off offset:256
	s_nop 1
	v_mul_f32_e32 v96, v101, v101
	v_fmac_f32_e32 v96, v100, v100
	v_fmac_f32_e32 v96, v102, v102
	v_fmac_f32_e32 v96, v103, v103
	v_fmac_f32_e32 v96, v106, v106
	v_fmac_f32_e32 v96, v107, v107
	v_fmac_f32_e32 v96, v104, v104
	v_fmac_f32_e32 v96, v105, v105
	v_add_f32_e32 v96, v120, v96
	ds_bpermute_b32 v97, v149, v96
	s_waitcnt lgkmcnt(0)
	v_add_f32_e32 v96, v96, v97
	ds_bpermute_b32 v97, v148, v96
	s_and_saveexec_b64 s[18:19], vcc
	s_cbranch_execz .LBB0_1910
	s_waitcnt lgkmcnt(0)
	v_add_f32_e32 v98, v96, v97
	v_lshlrev_b64 v[96:97], 6, v[112:113]
	v_lshl_add_u64 v[96:97], s[2:3], 0, v[96:97]
	v_lshl_add_u64 v[96:97], s[16:17], 2, v[96:97]
	s_lshl_b32 s24, s43, 2
	v_lshl_add_u64 v[96:97], v[96:97], 0, s[24:25]
	global_store_dword v[96:97], v98, off
.LBB0_1910:
	s_or_b64 exec, exec, s[18:19]
	v_or_b32_e32 v96, 32, v140
	s_waitcnt lgkmcnt(0)
	v_ashrrev_i32_e32 v97, 31, v96
	v_lshlrev_b64 v[98:99], 11, v[96:97]
	v_lshl_add_u64 v[98:99], s[4:5], 0, v[98:99]
	v_lshl_add_u64 v[102:103], v[138:139], 1, v[98:99]
	v_lshlrev_b32_e32 v104, 16, v174
	v_and_b32_e32 v105, 0xffff0000, v174
	v_lshlrev_b32_e32 v98, 16, v175
	v_and_b32_e32 v99, 0xffff0000, v175
	v_lshlrev_b32_e32 v106, 16, v176
	v_and_b32_e32 v107, 0xffff0000, v176
	v_lshlrev_b32_e32 v100, 16, v177
	v_and_b32_e32 v101, 0xffff0000, v177
	v_pk_add_f32 v[94:95], v[94:95], v[98:99]
	v_pk_add_f32 v[92:93], v[92:93], v[104:105]
	v_pk_add_f32 v[98:99], v[90:91], v[100:101]
	v_pk_add_f32 v[100:101], v[88:89], v[106:107]
	v_cvt_pk_bf16_f32 v88, v92, v93
	v_cvt_pk_bf16_f32 v89, v94, v95
	v_cvt_pk_bf16_f32 v90, v100, v101
	v_cvt_pk_bf16_f32 v91, v98, v99
	global_store_dwordx4 v[102:103], v[88:91], off
	v_mul_f32_e32 v104, v93, v93
	v_fmac_f32_e32 v104, v92, v92
	v_fmac_f32_e32 v104, v94, v94
	v_fmac_f32_e32 v104, v95, v95
	v_fmac_f32_e32 v104, v100, v100
	v_fmac_f32_e32 v104, v101, v101
	v_fmac_f32_e32 v104, v98, v98
	v_fmac_f32_e32 v104, v99, v99
	v_lshlrev_b32_e32 v92, 16, v178
	v_and_b32_e32 v93, 0xffff0000, v178
	v_lshlrev_b32_e32 v88, 16, v179
	v_and_b32_e32 v89, 0xffff0000, v179
	v_lshlrev_b32_e32 v94, 16, v180
	v_and_b32_e32 v95, 0xffff0000, v180
	v_lshlrev_b32_e32 v90, 16, v181
	v_and_b32_e32 v91, 0xffff0000, v181
	v_pk_add_f32 v[86:87], v[86:87], v[88:89]
	v_pk_add_f32 v[84:85], v[84:85], v[92:93]
	v_pk_add_f32 v[88:89], v[82:83], v[90:91]
	v_pk_add_f32 v[90:91], v[80:81], v[94:95]
	v_cvt_pk_bf16_f32 v80, v84, v85
	v_cvt_pk_bf16_f32 v81, v86, v87
	v_cvt_pk_bf16_f32 v82, v90, v91
	v_cvt_pk_bf16_f32 v83, v88, v89
	global_store_dwordx4 v[102:103], v[80:83], off offset:256
	s_nop 1
	v_mul_f32_e32 v80, v85, v85
	v_fmac_f32_e32 v80, v84, v84
	v_fmac_f32_e32 v80, v86, v86
	v_fmac_f32_e32 v80, v87, v87
	v_fmac_f32_e32 v80, v90, v90
	v_fmac_f32_e32 v80, v91, v91
	v_fmac_f32_e32 v80, v88, v88
	v_fmac_f32_e32 v80, v89, v89
	v_add_f32_e32 v80, v104, v80
	ds_bpermute_b32 v81, v149, v80
	s_waitcnt lgkmcnt(0)
	v_add_f32_e32 v80, v80, v81
	ds_bpermute_b32 v81, v148, v80
	s_and_saveexec_b64 s[18:19], vcc
	s_cbranch_execz .LBB0_1912
	s_waitcnt lgkmcnt(0)
	v_add_f32_e32 v82, v80, v81
	v_lshlrev_b64 v[80:81], 6, v[96:97]
	v_lshl_add_u64 v[80:81], s[2:3], 0, v[80:81]
	v_lshl_add_u64 v[80:81], s[16:17], 2, v[80:81]
	s_lshl_b32 s24, s43, 2
	v_lshl_add_u64 v[80:81], v[80:81], 0, s[24:25]
	global_store_dword v[80:81], v82, off
; DI float bf2f(unsigned v) { return __uint_as_float(v << 16); }
;   DI void operator()(const f32x4 (&acc)[2][2][4][2], const pg8::Unit& u, int wr, int wc, int fr_, int fq_) const {
;     ...
;             } else if (EPI == EPI_RESID) {
;               if (n == 0) {
;                 const int f8 = u.pn * 256 + bj * 128 + wc * 32 + 8 * fq;
;                 const f32x4 v1 = acc[ai][bj][m][1];
;                 f32x4 r0, r1;
;                 if (rsrc) {
;                   r0 = *(const f32x4*)(rsrc + (size_t)token * 1024 + f8); r1 = *(const f32x4*)(rsrc + (size_t)token * 1024 + f8 + 4);
;                 } else {
;                   const u32x4 xu = *(const u32x4*)(xr + (size_t)token * 1024 + f8);
;                   r0 = (f32x4){bf2f(xu.x & 0xffffu), bf2f(xu.x >> 16), bf2f(xu.y & 0xffffu), bf2f(xu.y >> 16)};
;                   r1 = (f32x4){bf2f(xu.z & 0xffffu), bf2f(xu.z >> 16), bf2f(xu.w & 0xffffu), bf2f(xu.w >> 16)};
;                 }
;                 r0 += v; r1 += v1;
;                 st_bf8(xr + (size_t)token * 1024 + f8, r0, r1, 1.f);
;                 ssq += r0[0] * r0[0] + r0[1] * r0[1] + r0[2] * r0[2] + r0[3] * r0[3] + r1[0] * r1[0] + r1[1] * r1[1] + r1[2] * r1[2] + r1[3] * r1[3];
;               }
;             } else {
;               if (n == 0) {
;                 const f32x4 v1 = acc[ai][bj][m][1];
;                 u32x4 o4;
;                 { const float t0 = fmaxf(v[0], 0.f) * rinv, t1 = fmaxf(v[1], 0.f) * rinv, t2 = fmaxf(v[2], 0.f) * rinv, t3 = fmaxf(v[3], 0.f) * rinv;
;                   o4.x = pack2(t0 * t0, t1 * t1); o4.y = pack2(t2 * t2, t3 * t3); }
;                 { const float t0 = fmaxf(v1[0], 0.f) * rinv, t1 = fmaxf(v1[1], 0.f) * rinv, t2 = fmaxf(v1[2], 0.f) * rinv, t3 = fmaxf(v1[3], 0.f) * rinv;
;                   o4.z = pack2(t0 * t0, t1 * t1); o4.w = pack2(t2 * t2, t3 * t3); }
;                 *(u32x4*)((u16*)big + (size_t)token * 4096 + u.pn * 256 + bj * 128 + wc * 32 + 8 * fq) = o4;
;               }
;             }
;           }
;         if (EPI == EPI_RESID) {
;           ssq += shx(ssq, 16, t_ & 63);
;           ssq += shx(ssq, 32, t_ & 63);
;           if (fq == 0) ss_out[(size_t)token * 16 + u.pn * 4 + wc] = ssq;
;         }
.LBB0_1912:
	s_or_b64 exec, exec, s[18:19]
	v_or_b32_e32 v80, 48, v140
	s_waitcnt lgkmcnt(0)
	v_ashrrev_i32_e32 v81, 31, v80
	v_lshlrev_b64 v[82:83], 11, v[80:81]
	v_lshl_add_u64 v[82:83], s[4:5], 0, v[82:83]
	v_lshl_add_u64 v[86:87], v[138:139], 1, v[82:83]
	v_lshlrev_b32_e32 v88, 16, v196
	v_and_b32_e32 v89, 0xffff0000, v196
	v_lshlrev_b32_e32 v82, 16, v197
	v_and_b32_e32 v83, 0xffff0000, v197
	v_lshlrev_b32_e32 v90, 16, v198
	v_and_b32_e32 v91, 0xffff0000, v198
	v_lshlrev_b32_e32 v84, 16, v199
	v_and_b32_e32 v85, 0xffff0000, v199
	v_pk_add_f32 v[78:79], v[78:79], v[82:83]
	v_pk_add_f32 v[76:77], v[76:77], v[88:89]
	v_pk_add_f32 v[82:83], v[74:75], v[84:85]
	v_pk_add_f32 v[84:85], v[72:73], v[90:91]
	v_cvt_pk_bf16_f32 v72, v76, v77
	v_cvt_pk_bf16_f32 v73, v78, v79
	v_cvt_pk_bf16_f32 v74, v84, v85
	v_cvt_pk_bf16_f32 v75, v82, v83
	global_store_dwordx4 v[86:87], v[72:75], off
	v_mul_f32_e32 v88, v77, v77
	v_fmac_f32_e32 v88, v76, v76
	v_fmac_f32_e32 v88, v78, v78
	v_fmac_f32_e32 v88, v79, v79
	v_fmac_f32_e32 v88, v84, v84
	v_fmac_f32_e32 v88, v85, v85
	v_fmac_f32_e32 v88, v82, v82
	v_fmac_f32_e32 v88, v83, v83
	v_lshlrev_b32_e32 v76, 16, v200
	v_and_b32_e32 v77, 0xffff0000, v200
	v_lshlrev_b32_e32 v72, 16, v201
	v_and_b32_e32 v73, 0xffff0000, v201
	v_lshlrev_b32_e32 v78, 16, v202
	v_and_b32_e32 v79, 0xffff0000, v202
	v_lshlrev_b32_e32 v74, 16, v203
	v_and_b32_e32 v75, 0xffff0000, v203
	v_pk_add_f32 v[70:71], v[70:71], v[72:73]
	v_pk_add_f32 v[68:69], v[68:69], v[76:77]
	v_pk_add_f32 v[72:73], v[66:67], v[74:75]
	v_pk_add_f32 v[74:75], v[64:65], v[78:79]
	v_cvt_pk_bf16_f32 v64, v68, v69
	v_cvt_pk_bf16_f32 v65, v70, v71
	v_cvt_pk_bf16_f32 v66, v74, v75
	v_cvt_pk_bf16_f32 v67, v72, v73
	global_store_dwordx4 v[86:87], v[64:67], off offset:256
	s_nop 1
	v_mul_f32_e32 v64, v69, v69
	v_fmac_f32_e32 v64, v68, v68
	v_fmac_f32_e32 v64, v70, v70
	v_fmac_f32_e32 v64, v71, v71
	v_fmac_f32_e32 v64, v74, v74
	v_fmac_f32_e32 v64, v75, v75
	v_fmac_f32_e32 v64, v72, v72
	v_fmac_f32_e32 v64, v73, v73
	v_add_f32_e32 v64, v88, v64
	ds_bpermute_b32 v65, v149, v64
	s_waitcnt lgkmcnt(0)
	v_add_f32_e32 v64, v64, v65
	ds_bpermute_b32 v65, v148, v64
	s_and_saveexec_b64 s[18:19], vcc
	v_readlane_b32 s51, v237, 11
	s_cbranch_execz .LBB0_1914
	s_waitcnt lgkmcnt(0)
	v_add_f32_e32 v66, v64, v65
	v_lshlrev_b64 v[64:65], 6, v[80:81]
	v_lshl_add_u64 v[64:65], s[2:3], 0, v[64:65]
	v_lshl_add_u64 v[64:65], s[16:17], 2, v[64:65]
	s_lshl_b32 s24, s43, 2
	v_lshl_add_u64 v[64:65], v[64:65], 0, s[24:25]
	global_store_dword v[64:65], v66, off
.LBB0_1914:
	s_or_b64 exec, exec, s[18:19]
	v_add_u32_e32 v64, 0x80, v140
	s_waitcnt lgkmcnt(0)
	v_ashrrev_i32_e32 v65, 31, v64
	v_lshlrev_b64 v[66:67], 11, v[64:65]
	v_lshl_add_u64 v[66:67], s[4:5], 0, v[66:67]
	v_lshl_add_u64 v[70:71], v[138:139], 1, v[66:67]
	v_lshlrev_b32_e32 v72, 16, v204
	v_and_b32_e32 v73, 0xffff0000, v204
	v_lshlrev_b32_e32 v66, 16, v205
	v_and_b32_e32 v67, 0xffff0000, v205
	v_lshlrev_b32_e32 v74, 16, v206
	v_and_b32_e32 v75, 0xffff0000, v206
	v_lshlrev_b32_e32 v68, 16, v207
	v_and_b32_e32 v69, 0xffff0000, v207
	v_pk_add_f32 v[62:63], v[62:63], v[66:67]
	v_pk_add_f32 v[60:61], v[60:61], v[72:73]
	v_pk_add_f32 v[66:67], v[58:59], v[68:69]
	v_pk_add_f32 v[68:69], v[56:57], v[74:75]
	v_cvt_pk_bf16_f32 v56, v60, v61
	v_cvt_pk_bf16_f32 v57, v62, v63
	v_cvt_pk_bf16_f32 v58, v68, v69
	v_cvt_pk_bf16_f32 v59, v66, v67
	global_store_dwordx4 v[70:71], v[56:59], off
	v_mul_f32_e32 v72, v61, v61
	v_fmac_f32_e32 v72, v60, v60
	v_fmac_f32_e32 v72, v62, v62
	v_fmac_f32_e32 v72, v63, v63
	v_fmac_f32_e32 v72, v68, v68
	v_fmac_f32_e32 v72, v69, v69
	v_fmac_f32_e32 v72, v66, v66
	v_fmac_f32_e32 v72, v67, v67
	v_lshlrev_b32_e32 v60, 16, v208
	v_and_b32_e32 v61, 0xffff0000, v208
	v_lshlrev_b32_e32 v56, 16, v209
	v_and_b32_e32 v57, 0xffff0000, v209
	v_lshlrev_b32_e32 v62, 16, v210
	v_and_b32_e32 v63, 0xffff0000, v210
	v_lshlrev_b32_e32 v58, 16, v211
	v_and_b32_e32 v59, 0xffff0000, v211
	v_pk_add_f32 v[54:55], v[54:55], v[56:57]
	v_pk_add_f32 v[52:53], v[52:53], v[60:61]
	v_pk_add_f32 v[56:57], v[50:51], v[58:59]
	v_pk_add_f32 v[58:59], v[48:49], v[62:63]
	v_cvt_pk_bf16_f32 v48, v52, v53
	v_cvt_pk_bf16_f32 v49, v54, v55
	v_cvt_pk_bf16_f32 v50, v58, v59
	v_cvt_pk_bf16_f32 v51, v56, v57
	global_store_dwordx4 v[70:71], v[48:51], off offset:256
	s_nop 1
	v_mul_f32_e32 v48, v53, v53
	v_fmac_f32_e32 v48, v52, v52
	v_fmac_f32_e32 v48, v54, v54
	v_fmac_f32_e32 v48, v55, v55
	v_fmac_f32_e32 v48, v58, v58
	v_fmac_f32_e32 v48, v59, v59
	v_fmac_f32_e32 v48, v56, v56
	v_fmac_f32_e32 v48, v57, v57
	v_add_f32_e32 v48, v72, v48
	ds_bpermute_b32 v49, v149, v48
	s_waitcnt lgkmcnt(0)
	v_add_f32_e32 v48, v48, v49
	ds_bpermute_b32 v49, v148, v48
	s_and_saveexec_b64 s[18:19], vcc
	s_cbranch_execz .LBB0_1916
	s_waitcnt lgkmcnt(0)
	v_add_f32_e32 v50, v48, v49
	v_lshlrev_b64 v[48:49], 6, v[64:65]
	v_lshl_add_u64 v[48:49], s[2:3], 0, v[48:49]
	v_lshl_add_u64 v[48:49], s[16:17], 2, v[48:49]
	s_lshl_b32 s24, s43, 2
	v_lshl_add_u64 v[48:49], v[48:49], 0, s[24:25]
	global_store_dword v[48:49], v50, off
; DI float bf2f(unsigned v) { return __uint_as_float(v << 16); }
;   DI void operator()(const f32x4 (&acc)[2][2][4][2], const pg8::Unit& u, int wr, int wc, int fr_, int fq_) const {
;     ...
;             } else if (EPI == EPI_RESID) {
;               if (n == 0) {
;                 const int f8 = u.pn * 256 + bj * 128 + wc * 32 + 8 * fq;
;                 const f32x4 v1 = acc[ai][bj][m][1];
;                 f32x4 r0, r1;
;                 if (rsrc) {
;                   r0 = *(const f32x4*)(rsrc + (size_t)token * 1024 + f8); r1 = *(const f32x4*)(rsrc + (size_t)token * 1024 + f8 + 4);
;                 } else {
;                   const u32x4 xu = *(const u32x4*)(xr + (size_t)token * 1024 + f8);
;                   r0 = (f32x4){bf2f(xu.x & 0xffffu), bf2f(xu.x >> 16), bf2f(xu.y & 0xffffu), bf2f(xu.y >> 16)};
;                   r1 = (f32x4){bf2f(xu.z & 0xffffu), bf2f(xu.z >> 16), bf2f(xu.w & 0xffffu), bf2f(xu.w >> 16)};
;                 }
;                 r0 += v; r1 += v1;
;                 st_bf8(xr + (size_t)token * 1024 + f8, r0, r1, 1.f);
;                 ssq += r0[0] * r0[0] + r0[1] * r0[1] + r0[2] * r0[2] + r0[3] * r0[3] + r1[0] * r1[0] + r1[1] * r1[1] + r1[2] * r1[2] + r1[3] * r1[3];
;               }
;             } else {
;               if (n == 0) {
;                 const f32x4 v1 = acc[ai][bj][m][1];
;                 u32x4 o4;
;                 { const float t0 = fmaxf(v[0], 0.f) * rinv, t1 = fmaxf(v[1], 0.f) * rinv, t2 = fmaxf(v[2], 0.f) * rinv, t3 = fmaxf(v[3], 0.f) * rinv;
;                   o4.x = pack2(t0 * t0, t1 * t1); o4.y = pack2(t2 * t2, t3 * t3); }
;                 { const float t0 = fmaxf(v1[0], 0.f) * rinv, t1 = fmaxf(v1[1], 0.f) * rinv, t2 = fmaxf(v1[2], 0.f) * rinv, t3 = fmaxf(v1[3], 0.f) * rinv;
;                   o4.z = pack2(t0 * t0, t1 * t1); o4.w = pack2(t2 * t2, t3 * t3); }
;                 *(u32x4*)((u16*)big + (size_t)token * 4096 + u.pn * 256 + bj * 128 + wc * 32 + 8 * fq) = o4;
;               }
;             }
;           }
;         if (EPI == EPI_RESID) {
;           ssq += shx(ssq, 16, t_ & 63);
;           ssq += shx(ssq, 32, t_ & 63);
;           if (fq == 0) ss_out[(size_t)token * 16 + u.pn * 4 + wc] = ssq;
;         }
.LBB0_1916:
	s_or_b64 exec, exec, s[18:19]
	v_add_u32_e32 v48, 0x90, v140
	s_waitcnt lgkmcnt(0)
	v_ashrrev_i32_e32 v49, 31, v48
	v_lshlrev_b64 v[50:51], 11, v[48:49]
	v_lshl_add_u64 v[50:51], s[4:5], 0, v[50:51]
	v_lshl_add_u64 v[54:55], v[138:139], 1, v[50:51]
	v_lshlrev_b32_e32 v56, 16, v212
	v_and_b32_e32 v57, 0xffff0000, v212
	v_lshlrev_b32_e32 v50, 16, v213
	v_and_b32_e32 v51, 0xffff0000, v213
	v_lshlrev_b32_e32 v58, 16, v214
	v_and_b32_e32 v59, 0xffff0000, v214
	v_lshlrev_b32_e32 v52, 16, v215
	v_and_b32_e32 v53, 0xffff0000, v215
	v_pk_add_f32 v[46:47], v[46:47], v[50:51]
	v_pk_add_f32 v[44:45], v[44:45], v[56:57]
	v_pk_add_f32 v[50:51], v[42:43], v[52:53]
	v_pk_add_f32 v[52:53], v[40:41], v[58:59]
	v_cvt_pk_bf16_f32 v40, v44, v45
	v_cvt_pk_bf16_f32 v41, v46, v47
	v_cvt_pk_bf16_f32 v42, v52, v53
	v_cvt_pk_bf16_f32 v43, v50, v51
	global_store_dwordx4 v[54:55], v[40:43], off
	v_mul_f32_e32 v56, v45, v45
	v_fmac_f32_e32 v56, v44, v44
	v_fmac_f32_e32 v56, v46, v46
	v_fmac_f32_e32 v56, v47, v47
	v_fmac_f32_e32 v56, v52, v52
	v_fmac_f32_e32 v56, v53, v53
	v_fmac_f32_e32 v56, v50, v50
	v_fmac_f32_e32 v56, v51, v51
	v_lshlrev_b32_e32 v44, 16, v216
	v_and_b32_e32 v45, 0xffff0000, v216
	v_lshlrev_b32_e32 v40, 16, v217
	v_and_b32_e32 v41, 0xffff0000, v217
	v_lshlrev_b32_e32 v46, 16, v218
	v_and_b32_e32 v47, 0xffff0000, v218
	v_lshlrev_b32_e32 v42, 16, v219
	v_and_b32_e32 v43, 0xffff0000, v219
	v_pk_add_f32 v[38:39], v[38:39], v[40:41]
	v_pk_add_f32 v[36:37], v[36:37], v[44:45]
	v_pk_add_f32 v[40:41], v[34:35], v[42:43]
	v_pk_add_f32 v[42:43], v[32:33], v[46:47]
	v_cvt_pk_bf16_f32 v32, v36, v37
	v_cvt_pk_bf16_f32 v33, v38, v39
	v_cvt_pk_bf16_f32 v34, v42, v43
	v_cvt_pk_bf16_f32 v35, v40, v41
	global_store_dwordx4 v[54:55], v[32:35], off offset:256
	s_nop 1
	v_mul_f32_e32 v32, v37, v37
	v_fmac_f32_e32 v32, v36, v36
	v_fmac_f32_e32 v32, v38, v38
	v_fmac_f32_e32 v32, v39, v39
	v_fmac_f32_e32 v32, v42, v42
	v_fmac_f32_e32 v32, v43, v43
	v_fmac_f32_e32 v32, v40, v40
	v_fmac_f32_e32 v32, v41, v41
	v_add_f32_e32 v32, v56, v32
	ds_bpermute_b32 v33, v149, v32
	s_waitcnt lgkmcnt(0)
	v_add_f32_e32 v32, v32, v33
	ds_bpermute_b32 v33, v148, v32
	s_and_saveexec_b64 s[18:19], vcc
	s_cbranch_execz .LBB0_1918
	s_waitcnt lgkmcnt(0)
	v_add_f32_e32 v34, v32, v33
	v_lshlrev_b64 v[32:33], 6, v[48:49]
	v_lshl_add_u64 v[32:33], s[2:3], 0, v[32:33]
	v_lshl_add_u64 v[32:33], s[16:17], 2, v[32:33]
	s_lshl_b32 s24, s43, 2
	v_lshl_add_u64 v[32:33], v[32:33], 0, s[24:25]
	global_store_dword v[32:33], v34, off
; DI float bf2f(unsigned v) { return __uint_as_float(v << 16); }
;   DI void operator()(const f32x4 (&acc)[2][2][4][2], const pg8::Unit& u, int wr, int wc, int fr_, int fq_) const {
;     ...
;             } else if (EPI == EPI_RESID) {
;               if (n == 0) {
;                 const int f8 = u.pn * 256 + bj * 128 + wc * 32 + 8 * fq;
;                 const f32x4 v1 = acc[ai][bj][m][1];
;                 f32x4 r0, r1;
;                 if (rsrc) {
;                   r0 = *(const f32x4*)(rsrc + (size_t)token * 1024 + f8); r1 = *(const f32x4*)(rsrc + (size_t)token * 1024 + f8 + 4);
;                 } else {
;                   const u32x4 xu = *(const u32x4*)(xr + (size_t)token * 1024 + f8);
;                   r0 = (f32x4){bf2f(xu.x & 0xffffu), bf2f(xu.x >> 16), bf2f(xu.y & 0xffffu), bf2f(xu.y >> 16)};
;                   r1 = (f32x4){bf2f(xu.z & 0xffffu), bf2f(xu.z >> 16), bf2f(xu.w & 0xffffu), bf2f(xu.w >> 16)};
;                 }
;                 r0 += v; r1 += v1;
;                 st_bf8(xr + (size_t)token * 1024 + f8, r0, r1, 1.f);
;                 ssq += r0[0] * r0[0] + r0[1] * r0[1] + r0[2] * r0[2] + r0[3] * r0[3] + r1[0] * r1[0] + r1[1] * r1[1] + r1[2] * r1[2] + r1[3] * r1[3];
;               }
;             } else {
;               if (n == 0) {
;                 const f32x4 v1 = acc[ai][bj][m][1];
;                 u32x4 o4;
;                 { const float t0 = fmaxf(v[0], 0.f) * rinv, t1 = fmaxf(v[1], 0.f) * rinv, t2 = fmaxf(v[2], 0.f) * rinv, t3 = fmaxf(v[3], 0.f) * rinv;
;                   o4.x = pack2(t0 * t0, t1 * t1); o4.y = pack2(t2 * t2, t3 * t3); }
;                 { const float t0 = fmaxf(v1[0], 0.f) * rinv, t1 = fmaxf(v1[1], 0.f) * rinv, t2 = fmaxf(v1[2], 0.f) * rinv, t3 = fmaxf(v1[3], 0.f) * rinv;
;                   o4.z = pack2(t0 * t0, t1 * t1); o4.w = pack2(t2 * t2, t3 * t3); }
;                 *(u32x4*)((u16*)big + (size_t)token * 4096 + u.pn * 256 + bj * 128 + wc * 32 + 8 * fq) = o4;
;               }
;             }
;           }
;         if (EPI == EPI_RESID) {
;           ssq += shx(ssq, 16, t_ & 63);
;           ssq += shx(ssq, 32, t_ & 63);
;           if (fq == 0) ss_out[(size_t)token * 16 + u.pn * 4 + wc] = ssq;
;         }
.LBB0_1918:
	s_or_b64 exec, exec, s[18:19]
	v_add_u32_e32 v32, 0xa0, v140
	s_waitcnt lgkmcnt(0)
	v_ashrrev_i32_e32 v33, 31, v32
	v_lshlrev_b64 v[34:35], 11, v[32:33]
	v_lshl_add_u64 v[34:35], s[4:5], 0, v[34:35]
	v_lshl_add_u64 v[38:39], v[138:139], 1, v[34:35]
	v_lshlrev_b32_e32 v40, 16, v220
	v_and_b32_e32 v41, 0xffff0000, v220
	v_lshlrev_b32_e32 v34, 16, v221
	v_and_b32_e32 v35, 0xffff0000, v221
	v_lshlrev_b32_e32 v42, 16, v222
	v_and_b32_e32 v43, 0xffff0000, v222
	v_lshlrev_b32_e32 v36, 16, v223
	v_and_b32_e32 v37, 0xffff0000, v223
	v_pk_add_f32 v[30:31], v[30:31], v[34:35]
	v_pk_add_f32 v[28:29], v[28:29], v[40:41]
	v_pk_add_f32 v[34:35], v[26:27], v[36:37]
	v_pk_add_f32 v[36:37], v[24:25], v[42:43]
	v_cvt_pk_bf16_f32 v24, v28, v29
	v_cvt_pk_bf16_f32 v25, v30, v31
	v_cvt_pk_bf16_f32 v26, v36, v37
	v_cvt_pk_bf16_f32 v27, v34, v35
	global_store_dwordx4 v[38:39], v[24:27], off
	v_mul_f32_e32 v40, v29, v29
	v_fmac_f32_e32 v40, v28, v28
	v_fmac_f32_e32 v40, v30, v30
	v_fmac_f32_e32 v40, v31, v31
	v_fmac_f32_e32 v40, v36, v36
	v_fmac_f32_e32 v40, v37, v37
	v_fmac_f32_e32 v40, v34, v34
	v_fmac_f32_e32 v40, v35, v35
	v_lshlrev_b32_e32 v28, 16, v224
	v_and_b32_e32 v29, 0xffff0000, v224
	v_lshlrev_b32_e32 v24, 16, v225
	v_and_b32_e32 v25, 0xffff0000, v225
	v_lshlrev_b32_e32 v30, 16, v226
	v_and_b32_e32 v31, 0xffff0000, v226
	v_lshlrev_b32_e32 v26, 16, v227
	v_and_b32_e32 v27, 0xffff0000, v227
	v_pk_add_f32 v[22:23], v[22:23], v[24:25]
	v_pk_add_f32 v[20:21], v[20:21], v[28:29]
	v_pk_add_f32 v[24:25], v[18:19], v[26:27]
	v_pk_add_f32 v[26:27], v[16:17], v[30:31]
	v_cvt_pk_bf16_f32 v16, v20, v21
	v_cvt_pk_bf16_f32 v17, v22, v23
	v_cvt_pk_bf16_f32 v18, v26, v27
	v_cvt_pk_bf16_f32 v19, v24, v25
	global_store_dwordx4 v[38:39], v[16:19], off offset:256
	s_nop 1
	v_mul_f32_e32 v16, v21, v21
	v_fmac_f32_e32 v16, v20, v20
	v_fmac_f32_e32 v16, v22, v22
	v_fmac_f32_e32 v16, v23, v23
	v_fmac_f32_e32 v16, v26, v26
	v_fmac_f32_e32 v16, v27, v27
	v_fmac_f32_e32 v16, v24, v24
	v_fmac_f32_e32 v16, v25, v25
	v_add_f32_e32 v16, v40, v16
	ds_bpermute_b32 v17, v149, v16
	s_waitcnt lgkmcnt(0)
	v_add_f32_e32 v16, v16, v17
	ds_bpermute_b32 v17, v148, v16
	s_and_saveexec_b64 s[18:19], vcc
	s_cbranch_execz .LBB0_1920
	s_waitcnt lgkmcnt(0)
	v_add_f32_e32 v18, v16, v17
	v_lshlrev_b64 v[16:17], 6, v[32:33]
	v_lshl_add_u64 v[16:17], s[2:3], 0, v[16:17]
	v_lshl_add_u64 v[16:17], s[16:17], 2, v[16:17]
	s_lshl_b32 s24, s43, 2
	v_lshl_add_u64 v[16:17], v[16:17], 0, s[24:25]
	global_store_dword v[16:17], v18, off
.LBB0_1920:
	s_or_b64 exec, exec, s[18:19]
	v_add_u32_e32 v16, 0xb0, v140
	s_waitcnt lgkmcnt(0)
	v_ashrrev_i32_e32 v17, 31, v16
	v_lshlrev_b64 v[18:19], 11, v[16:17]
	v_lshl_add_u64 v[18:19], s[4:5], 0, v[18:19]
	v_lshl_add_u64 v[22:23], v[138:139], 1, v[18:19]
	v_lshlrev_b32_e32 v24, 16, v228
	v_and_b32_e32 v25, 0xffff0000, v228
	v_lshlrev_b32_e32 v18, 16, v229
	v_and_b32_e32 v19, 0xffff0000, v229
	v_lshlrev_b32_e32 v26, 16, v230
	v_and_b32_e32 v27, 0xffff0000, v230
	v_lshlrev_b32_e32 v20, 16, v231
	v_and_b32_e32 v21, 0xffff0000, v231
	v_pk_add_f32 v[14:15], v[14:15], v[18:19]
	v_pk_add_f32 v[12:13], v[12:13], v[24:25]
	v_pk_add_f32 v[18:19], v[10:11], v[20:21]
	v_pk_add_f32 v[20:21], v[8:9], v[26:27]
	v_cvt_pk_bf16_f32 v8, v12, v13
	v_cvt_pk_bf16_f32 v9, v14, v15
	v_cvt_pk_bf16_f32 v10, v20, v21
	v_cvt_pk_bf16_f32 v11, v18, v19
	global_store_dwordx4 v[22:23], v[8:11], off
	v_mul_f32_e32 v24, v13, v13
	v_fmac_f32_e32 v24, v12, v12
	v_fmac_f32_e32 v24, v14, v14
	v_fmac_f32_e32 v24, v15, v15
	v_fmac_f32_e32 v24, v20, v20
	v_fmac_f32_e32 v24, v21, v21
	v_fmac_f32_e32 v24, v18, v18
	v_fmac_f32_e32 v24, v19, v19
	v_lshlrev_b32_e32 v12, 16, v232
	v_and_b32_e32 v13, 0xffff0000, v232
	v_lshlrev_b32_e32 v8, 16, v233
	v_and_b32_e32 v9, 0xffff0000, v233
	v_lshlrev_b32_e32 v14, 16, v234
	v_and_b32_e32 v15, 0xffff0000, v234
	v_lshlrev_b32_e32 v10, 16, v235
	v_and_b32_e32 v11, 0xffff0000, v235
	v_pk_add_f32 v[6:7], v[6:7], v[8:9]
	v_pk_add_f32 v[4:5], v[4:5], v[12:13]
	v_pk_add_f32 v[8:9], v[2:3], v[10:11]
	v_pk_add_f32 v[10:11], v[0:1], v[14:15]
	v_cvt_pk_bf16_f32 v0, v4, v5
	v_cvt_pk_bf16_f32 v1, v6, v7
	v_cvt_pk_bf16_f32 v2, v10, v11
	v_cvt_pk_bf16_f32 v3, v8, v9
	global_store_dwordx4 v[22:23], v[0:3], off offset:256
	s_nop 1
	v_mul_f32_e32 v0, v5, v5
	v_fmac_f32_e32 v0, v4, v4
	v_fmac_f32_e32 v0, v6, v6
	v_fmac_f32_e32 v0, v7, v7
	v_fmac_f32_e32 v0, v10, v10
	v_fmac_f32_e32 v0, v11, v11
	v_fmac_f32_e32 v0, v8, v8
	v_fmac_f32_e32 v0, v9, v9
	v_add_f32_e32 v0, v24, v0
	ds_bpermute_b32 v1, v149, v0
	s_waitcnt lgkmcnt(0)
	v_add_f32_e32 v0, v0, v1
	ds_bpermute_b32 v1, v148, v0
	s_and_saveexec_b64 s[18:19], vcc
	s_cbranch_execz .LBB0_1897
	s_waitcnt lgkmcnt(0)
	v_add_f32_e32 v2, v0, v1
	v_lshlrev_b64 v[0:1], 6, v[16:17]
	v_lshl_add_u64 v[0:1], s[2:3], 0, v[0:1]
	v_lshl_add_u64 v[0:1], s[16:17], 2, v[0:1]
	s_lshl_b32 s24, s43, 2
	v_lshl_add_u64 v[0:1], v[0:1], 0, s[24:25]
	global_store_dword v[0:1], v2, off
	s_branch .LBB0_1897
